# gate values for write_y prefetched before the SB/SWA tile loops (on top of SB XCD remap, 7-tile window, back-to-back sel loads)
# speedup vs baseline: 1.0131x; 1.0049x over previous
; DI unsigned cvtpk(float lo, float hi) { typedef float f2 __attribute__((ext_vector_type(2))); typedef __bf16 b2 __attribute__((ext_vector_type(2))); f2 v = {lo, hi}; b2 b = __builtin_convertvector(v, b2); return __builtin_bit_cast(unsigned, b); }
; DI float bflo(unsigned w) { return __uint_as_float(w << 16); }
; DI float bfhi(unsigned w) { return __uint_as_float(w & 0xffff0000u); }
; DI float silu_(float g) { return g * fast_rcp(1.f + fast_exp2(-g * LOG2E)); }
; DI void write_y(const f32x16& o0, const f32x16& o1, float scale, const bf16_t* grow, bf16_t* yrow, int h) {
; #pragma unroll
;     for (int dh = 0; dh < 2; ++dh) {
;         u32x2 w[4];
; #pragma unroll
;         for (int grp = 0; grp < 4; ++grp) {
;             const int d0 = 32 * dh + 8 * grp + 4 * h;
;             const u32x2 g = *(const u32x2*)(grow + d0);
;             const f32x16& o = dh ? o1 : o0;
;             const float y0 = o[4 * grp + 0] * scale * silu_(bflo(g.x)), y1 = o[4 * grp + 1] * scale * silu_(bfhi(g.x));
;             const float y2 = o[4 * grp + 2] * scale * silu_(bflo(g.y)), y3 = o[4 * grp + 3] * scale * silu_(bfhi(g.y));
;             w[grp].x = cvtpk(y0, y1); w[grp].y = cvtpk(y2, y3);
;         }
;         store_pair16(yrow + 32 * dh, w[0], w[1], 0, h);
;         store_pair16(yrow + 32 * dh, w[2], w[3], 1, h);
;     }
; }
.LBB0_333:
	s_add_i32 s17, s17, s78
	s_cmpk_gt_i32 s17, 0x3ff
	s_waitcnt vmcnt(0)
	v_lshlrev_b32_e32 v58, 16, v160
	v_and_b32_e32 v59, 0xffff0000, v160
	v_lshlrev_b32_e32 v60, 16, v161
	v_and_b32_e32 v61, 0xffff0000, v161
	v_mul_f32_e32 v62, 0xbfb8aa3b, v58
	v_mul_f32_e32 v63, 0xbfb8aa3b, v59
	v_mul_f32_e32 v64, 0xbfb8aa3b, v60
	v_mul_f32_e32 v65, 0xbfb8aa3b, v61
	v_exp_f32_e32 v62, v62
	v_exp_f32_e32 v63, v63
	v_exp_f32_e32 v64, v64
	v_exp_f32_e32 v65, v65
	v_add_f32_e32 v62, 1.0, v62
	v_add_f32_e32 v63, 1.0, v63
	v_add_f32_e32 v64, 1.0, v64
	v_add_f32_e32 v65, 1.0, v65
	v_rcp_f32_e32 v62, v62
	v_rcp_f32_e32 v63, v63
	v_rcp_f32_e32 v64, v64
	v_rcp_f32_e32 v65, v65
	v_mul_f32_e32 v58, v62, v58
	v_mul_f32_e32 v59, v63, v59
	v_mul_f32_e32 v60, v64, v60
	v_mul_f32_e32 v61, v65, v61
	v_mul_f32_e32 v18, v18, v58
	v_mul_f32_e32 v19, v19, v59
	v_mul_f32_e32 v20, v20, v60
	v_mul_f32_e32 v21, v21, v61
	v_cvt_pk_bf16_f32 v18, v18, v19
	v_cvt_pk_bf16_f32 v19, v20, v21
	v_lshlrev_b32_e32 v58, 16, v162
	v_and_b32_e32 v59, 0xffff0000, v162
	v_lshlrev_b32_e32 v60, 16, v163
	v_and_b32_e32 v61, 0xffff0000, v163
	v_mul_f32_e32 v62, 0xbfb8aa3b, v58
	v_mul_f32_e32 v63, 0xbfb8aa3b, v59
	v_mul_f32_e32 v64, 0xbfb8aa3b, v60
	v_mul_f32_e32 v65, 0xbfb8aa3b, v61
	v_exp_f32_e32 v62, v62
	v_exp_f32_e32 v63, v63
	v_exp_f32_e32 v64, v64
	v_exp_f32_e32 v65, v65
	v_add_f32_e32 v62, 1.0, v62
	v_add_f32_e32 v63, 1.0, v63
	v_add_f32_e32 v64, 1.0, v64
	v_add_f32_e32 v65, 1.0, v65
	v_rcp_f32_e32 v62, v62
	v_rcp_f32_e32 v63, v63
	v_rcp_f32_e32 v64, v64
	v_rcp_f32_e32 v65, v65
	v_mul_f32_e32 v58, v62, v58
	v_mul_f32_e32 v59, v63, v59
	v_mul_f32_e32 v60, v64, v60
	v_mul_f32_e32 v61, v65, v61
	v_mul_f32_e32 v22, v22, v58
	v_mul_f32_e32 v23, v23, v59
	v_mul_f32_e32 v24, v24, v60
	v_mul_f32_e32 v25, v25, v61
	v_cvt_pk_bf16_f32 v20, v22, v23
	v_cvt_pk_bf16_f32 v21, v24, v25
	s_nop 1
	v_permlane32_swap_b32_e32 v18, v20
	v_permlane32_swap_b32_e32 v19, v21
	global_store_dwordx4 v[84:85], v[18:21], off
	v_lshlrev_b32_e32 v58, 16, v164
	v_and_b32_e32 v59, 0xffff0000, v164
	v_lshlrev_b32_e32 v60, 16, v165
	v_and_b32_e32 v61, 0xffff0000, v165
	v_mul_f32_e32 v62, 0xbfb8aa3b, v58
	v_mul_f32_e32 v63, 0xbfb8aa3b, v59
	v_mul_f32_e32 v64, 0xbfb8aa3b, v60
	v_mul_f32_e32 v65, 0xbfb8aa3b, v61
	v_exp_f32_e32 v62, v62
	v_exp_f32_e32 v63, v63
	v_exp_f32_e32 v64, v64
	v_exp_f32_e32 v65, v65
	v_add_f32_e32 v62, 1.0, v62
	v_add_f32_e32 v63, 1.0, v63
	v_add_f32_e32 v64, 1.0, v64
	v_add_f32_e32 v65, 1.0, v65
	v_rcp_f32_e32 v62, v62
	v_rcp_f32_e32 v63, v63
	v_rcp_f32_e32 v64, v64
	v_rcp_f32_e32 v65, v65
	v_mul_f32_e32 v58, v62, v58
	v_mul_f32_e32 v59, v63, v59
	v_mul_f32_e32 v60, v64, v60
	v_mul_f32_e32 v61, v65, v61
	v_mul_f32_e32 v26, v26, v58
	v_mul_f32_e32 v27, v27, v59
	v_mul_f32_e32 v28, v28, v60
	v_mul_f32_e32 v29, v29, v61
	v_cvt_pk_bf16_f32 v26, v26, v27
	v_cvt_pk_bf16_f32 v27, v28, v29
	v_lshlrev_b32_e32 v58, 16, v166
	v_and_b32_e32 v59, 0xffff0000, v166
	v_lshlrev_b32_e32 v60, 16, v167
	v_and_b32_e32 v61, 0xffff0000, v167
	v_mul_f32_e32 v62, 0xbfb8aa3b, v58
	v_mul_f32_e32 v63, 0xbfb8aa3b, v59
	v_mul_f32_e32 v64, 0xbfb8aa3b, v60
	v_mul_f32_e32 v65, 0xbfb8aa3b, v61
	v_exp_f32_e32 v62, v62
	v_exp_f32_e32 v63, v63
	v_exp_f32_e32 v64, v64
	v_exp_f32_e32 v65, v65
	v_add_f32_e32 v62, 1.0, v62
	v_add_f32_e32 v63, 1.0, v63
	v_add_f32_e32 v64, 1.0, v64
	v_add_f32_e32 v65, 1.0, v65
	v_rcp_f32_e32 v62, v62
	v_rcp_f32_e32 v63, v63
	v_rcp_f32_e32 v64, v64
	v_rcp_f32_e32 v65, v65
	v_mul_f32_e32 v58, v62, v58
	v_mul_f32_e32 v59, v63, v59
	v_mul_f32_e32 v60, v64, v60
	v_mul_f32_e32 v61, v65, v61
	v_mul_f32_e32 v30, v30, v58
	v_mul_f32_e32 v31, v31, v59
	v_mul_f32_e32 v32, v32, v60
	v_mul_f32_e32 v33, v33, v61
	v_cvt_pk_bf16_f32 v28, v30, v31
	v_cvt_pk_bf16_f32 v29, v32, v33
	s_nop 1
	v_permlane32_swap_b32_e32 v26, v28
	v_permlane32_swap_b32_e32 v27, v29
; DI unsigned cvtpk(float lo, float hi) { typedef float f2 __attribute__((ext_vector_type(2))); typedef __bf16 b2 __attribute__((ext_vector_type(2))); f2 v = {lo, hi}; b2 b = __builtin_convertvector(v, b2); return __builtin_bit_cast(unsigned, b); }
; DI float bflo(unsigned w) { return __uint_as_float(w << 16); }
; DI float bfhi(unsigned w) { return __uint_as_float(w & 0xffff0000u); }
; DI float silu_(float g) { return g * fast_rcp(1.f + fast_exp2(-g * LOG2E)); }
; DI void write_y(const f32x16& o0, const f32x16& o1, float scale, const bf16_t* grow, bf16_t* yrow, int h) {
; #pragma unroll
;     for (int dh = 0; dh < 2; ++dh) {
;         u32x2 w[4];
; #pragma unroll
;         for (int grp = 0; grp < 4; ++grp) {
;             const int d0 = 32 * dh + 8 * grp + 4 * h;
;             const u32x2 g = *(const u32x2*)(grow + d0);
;             const f32x16& o = dh ? o1 : o0;
;             const float y0 = o[4 * grp + 0] * scale * silu_(bflo(g.x)), y1 = o[4 * grp + 1] * scale * silu_(bfhi(g.x));
;             const float y2 = o[4 * grp + 2] * scale * silu_(bflo(g.y)), y3 = o[4 * grp + 3] * scale * silu_(bfhi(g.y));
;             w[grp].x = cvtpk(y0, y1); w[grp].y = cvtpk(y2, y3);
;         }
;         store_pair16(yrow + 32 * dh, w[0], w[1], 0, h);
;         store_pair16(yrow + 32 * dh, w[2], w[3], 1, h);
;     }
; }
	global_store_dwordx4 v[84:85], v[26:29], off offset:32
	v_lshlrev_b32_e32 v58, 16, v168
	v_and_b32_e32 v59, 0xffff0000, v168
	v_lshlrev_b32_e32 v60, 16, v169
	v_and_b32_e32 v61, 0xffff0000, v169
	v_mul_f32_e32 v62, 0xbfb8aa3b, v58
	v_mul_f32_e32 v63, 0xbfb8aa3b, v59
	v_mul_f32_e32 v64, 0xbfb8aa3b, v60
	v_mul_f32_e32 v65, 0xbfb8aa3b, v61
	v_exp_f32_e32 v62, v62
	v_exp_f32_e32 v63, v63
	v_exp_f32_e32 v64, v64
	v_exp_f32_e32 v65, v65
	v_add_f32_e32 v62, 1.0, v62
	v_add_f32_e32 v63, 1.0, v63
	v_add_f32_e32 v64, 1.0, v64
	v_add_f32_e32 v65, 1.0, v65
	v_rcp_f32_e32 v62, v62
	v_rcp_f32_e32 v63, v63
	v_rcp_f32_e32 v64, v64
	v_rcp_f32_e32 v65, v65
	v_mul_f32_e32 v58, v62, v58
	v_mul_f32_e32 v59, v63, v59
	v_mul_f32_e32 v60, v64, v60
	v_mul_f32_e32 v61, v65, v61
	v_mul_f32_e32 v2, v2, v58
	v_mul_f32_e32 v3, v3, v59
	v_mul_f32_e32 v4, v4, v60
	v_mul_f32_e32 v5, v5, v61
	v_cvt_pk_bf16_f32 v2, v2, v3
	v_cvt_pk_bf16_f32 v3, v4, v5
	v_lshlrev_b32_e32 v58, 16, v170
	v_and_b32_e32 v59, 0xffff0000, v170
	v_lshlrev_b32_e32 v60, 16, v171
	v_and_b32_e32 v61, 0xffff0000, v171
	v_mul_f32_e32 v62, 0xbfb8aa3b, v58
	v_mul_f32_e32 v63, 0xbfb8aa3b, v59
	v_mul_f32_e32 v64, 0xbfb8aa3b, v60
	v_mul_f32_e32 v65, 0xbfb8aa3b, v61
	v_exp_f32_e32 v62, v62
	v_exp_f32_e32 v63, v63
	v_exp_f32_e32 v64, v64
	v_exp_f32_e32 v65, v65
	v_add_f32_e32 v62, 1.0, v62
	v_add_f32_e32 v63, 1.0, v63
	v_add_f32_e32 v64, 1.0, v64
	v_add_f32_e32 v65, 1.0, v65
	v_rcp_f32_e32 v62, v62
	v_rcp_f32_e32 v63, v63
	v_rcp_f32_e32 v64, v64
	v_rcp_f32_e32 v65, v65
	v_mul_f32_e32 v58, v62, v58
	v_mul_f32_e32 v59, v63, v59
	v_mul_f32_e32 v60, v64, v60
	v_mul_f32_e32 v61, v65, v61
	v_mul_f32_e32 v6, v6, v58
	v_mul_f32_e32 v7, v7, v59
	v_mul_f32_e32 v8, v8, v60
	v_mul_f32_e32 v9, v9, v61
	v_cvt_pk_bf16_f32 v4, v6, v7
	v_cvt_pk_bf16_f32 v5, v8, v9
	s_nop 1
	v_permlane32_swap_b32_e32 v2, v4
	v_permlane32_swap_b32_e32 v3, v5
	global_store_dwordx4 v[84:85], v[2:5], off offset:64
	v_lshlrev_b32_e32 v58, 16, v172
	v_and_b32_e32 v59, 0xffff0000, v172
	v_lshlrev_b32_e32 v60, 16, v173
	v_and_b32_e32 v61, 0xffff0000, v173
	v_mul_f32_e32 v62, 0xbfb8aa3b, v58
	v_mul_f32_e32 v63, 0xbfb8aa3b, v59
	v_mul_f32_e32 v64, 0xbfb8aa3b, v60
	v_mul_f32_e32 v65, 0xbfb8aa3b, v61
	v_exp_f32_e32 v62, v62
	v_exp_f32_e32 v63, v63
	v_exp_f32_e32 v64, v64
	v_exp_f32_e32 v65, v65
	v_add_f32_e32 v62, 1.0, v62
	v_add_f32_e32 v63, 1.0, v63
	v_add_f32_e32 v64, 1.0, v64
	v_add_f32_e32 v65, 1.0, v65
	v_rcp_f32_e32 v62, v62
	v_rcp_f32_e32 v63, v63
	v_rcp_f32_e32 v64, v64
	v_rcp_f32_e32 v65, v65
	v_mul_f32_e32 v58, v62, v58
	v_mul_f32_e32 v59, v63, v59
	v_mul_f32_e32 v60, v64, v60
	v_mul_f32_e32 v61, v65, v61
	v_mul_f32_e32 v10, v10, v58
	v_mul_f32_e32 v11, v11, v59
	v_mul_f32_e32 v12, v12, v60
	v_mul_f32_e32 v13, v13, v61
	v_cvt_pk_bf16_f32 v10, v10, v11
	v_cvt_pk_bf16_f32 v11, v12, v13
	v_lshlrev_b32_e32 v58, 16, v174
	v_and_b32_e32 v59, 0xffff0000, v174
	v_lshlrev_b32_e32 v60, 16, v175
	v_and_b32_e32 v61, 0xffff0000, v175
	v_mul_f32_e32 v62, 0xbfb8aa3b, v58
	v_mul_f32_e32 v63, 0xbfb8aa3b, v59
	v_mul_f32_e32 v64, 0xbfb8aa3b, v60
	v_mul_f32_e32 v65, 0xbfb8aa3b, v61
	v_exp_f32_e32 v62, v62
	v_exp_f32_e32 v63, v63
	v_exp_f32_e32 v64, v64
	v_exp_f32_e32 v65, v65
	v_add_f32_e32 v62, 1.0, v62
	v_add_f32_e32 v63, 1.0, v63
	v_add_f32_e32 v64, 1.0, v64
	v_add_f32_e32 v65, 1.0, v65
	v_rcp_f32_e32 v62, v62
	v_rcp_f32_e32 v63, v63
	v_rcp_f32_e32 v64, v64
	v_rcp_f32_e32 v65, v65
	v_mul_f32_e32 v58, v62, v58
	v_mul_f32_e32 v59, v63, v59
	v_mul_f32_e32 v60, v64, v60
	v_mul_f32_e32 v61, v65, v61
	v_mul_f32_e32 v14, v14, v58
	v_mul_f32_e32 v15, v15, v59
	v_mul_f32_e32 v16, v16, v60
	v_mul_f32_e32 v17, v17, v61
	v_cvt_pk_bf16_f32 v12, v14, v15
	v_cvt_pk_bf16_f32 v13, v16, v17
	s_nop 1
	v_permlane32_swap_b32_e32 v10, v12
	v_permlane32_swap_b32_e32 v11, v13
	global_store_dwordx4 v[84:85], v[10:13], off offset:96
	s_cbranch_scc1 .LBB0_358

; #define LAS __attribute__((address_space(3)))
; DI float fast_exp2(float x) { return __builtin_amdgcn_exp2f(x); }
; DI float fast_rcp(float x) { return __builtin_amdgcn_rcpf(x); }
; DI void sb_wg_unit(bf16_t* act, int b, int hh, int Qb, LAS unsigned char* lds, volatile LAS unsigned* ctl, int tid, int wid, int lane) {
;     ...
;         __syncthreads();
;         if (tid == 0) ctl[7] = 0u;
;         coop_load_tiles(kgb, C_VA - C_KA, t_top, nt, lds, wid, lane);
;         __syncthreads();
; #pragma unroll 1
;         while (!done && t >= t_bot) {
;             const int kv0 = t * 64;
;             LAS const unsigned char* Ks = lds + (t_top - t) * 16384; LAS const unsigned char* Vs = Ks + 8192;
;             f32x16 p0, p1;
; #pragma unroll
;             for (int i = 0; i < 16; ++i) { p0[i] = 0.f; p1[i] = 0.f; }
;             qk_tile(p0, p1, Ks, qf, r, h);
;             const bool diag = (kv0 + 63 >= q0);
;             f32x16 F0, F1;
; #pragma unroll
;             for (int i = 0; i < 16; ++i) {
;                 const int kl = (i & 3) + 8 * (i >> 2) + 4 * h;
;                 { const float e = fast_exp2(fminf(p0[i], 60.f)); const float f = fast_rcp(1.f + e);
;                   const bool valid = !diag || (kv0 + kl < qpos); F0[i] = valid ? f : 1.f; p0[i] = valid ? e * f : 0.f; }
;                 { const float e = fast_exp2(fminf(p1[i], 60.f)); const float f = fast_rcp(1.f + e);
;                   const bool valid = !diag || (kv0 + 32 + kl < qpos); F1[i] = valid ? f : 1.f; p1[i] = valid ? e * f : 0.f; }
.LBB0_353:
	s_cmp_lt_i32 s24, s23
	s_cselect_b64 s[10:11], -1, 0
	s_or_b64 s[10:11], s[8:9], s[10:11]
	s_and_b64 vcc, exec, s[10:11]
	s_waitcnt lgkmcnt(0)
	s_barrier
	v_lshlrev_b32_e32 v142, 1, v82
	v_mov_b32_e32 v143, v1
	v_lshl_add_u64 v[142:143], v[88:89], 0, v[142:143]
	global_load_dwordx2 v[160:161], v[142:143], off offset:3072
	global_load_dwordx2 v[162:163], v[142:143], off offset:3088
	global_load_dwordx2 v[164:165], v[142:143], off offset:3104
	global_load_dwordx2 v[166:167], v[142:143], off offset:3120
	global_load_dwordx2 v[168:169], v[142:143], off offset:3136
	global_load_dwordx2 v[170:171], v[142:143], off offset:3152
	global_load_dwordx2 v[172:173], v[142:143], off offset:3168
	global_load_dwordx2 v[174:175], v[142:143], off offset:3184
	s_cbranch_vccnz .LBB0_356
	s_lshl_b32 s8, s24, 6
	s_or_b32 s12, s8, 63
	s_lshl_b32 s8, s24, 14
	s_lshl_b32 s13, s25, 14
	v_subrev_u32_e32 v87, s8, v95
	v_subrev_u32_e32 v97, s8, v96
.LBB0_355:
	v_add_u32_e32 v90, s13, v97
	ds_read_b128 v[34:37], v90
	ds_read_b128 v[38:41], v90 offset:512
	ds_read_b128 v[100:103], v90 offset:2048
	ds_read_b128 v[108:111], v90 offset:2560
	s_cmp_lt_i32 s12, s21
	s_cselect_b64 s[8:9], -1, 0
	s_waitcnt vmcnt(8) lgkmcnt(3)
	v_mfma_f32_32x32x16_bf16 v[50:65], v[34:37], v[66:69], 0
	s_mov_b32 s10, s24
	v_add_u32_e32 v97, 0x4000, v97
	s_waitcnt lgkmcnt(2)
	v_mfma_f32_32x32x16_bf16 v[34:49], v[38:41], v[66:69], 0
	s_waitcnt lgkmcnt(1)
	v_mfma_f32_32x32x16_bf16 v[50:65], v[100:103], v[70:73], v[50:65]
	s_waitcnt lgkmcnt(0)
	v_mfma_f32_32x32x16_bf16 v[34:49], v[108:111], v[70:73], v[34:49]
	ds_read_b128 v[100:103], v90 offset:4096
	ds_read_b128 v[108:111], v90 offset:4608
	s_waitcnt lgkmcnt(1)
	v_mfma_f32_32x32x16_bf16 v[50:65], v[100:103], v[74:77], v[50:65]
	s_waitcnt lgkmcnt(0)
	v_mfma_f32_32x32x16_bf16 v[34:49], v[108:111], v[74:77], v[34:49]
	ds_read_b128 v[100:103], v90 offset:6144
	ds_read_b128 v[108:111], v90 offset:6656
	v_add_u32_e32 v90, s12, v82
	v_subrev_u32_e32 v98, 63, v90
	v_cmp_lt_i32_e32 vcc, v98, v86
	s_or_b64 vcc, s[8:9], vcc
	s_waitcnt lgkmcnt(1)
	v_mfma_f32_32x32x16_bf16 v[50:65], v[100:103], v[78:81], v[50:65]
	v_subrev_u32_e32 v103, 30, v90
	s_waitcnt lgkmcnt(0)
	v_mfma_f32_32x32x16_bf16 v[34:49], v[108:111], v[78:81], v[34:49]
	s_nop 8
	v_max_f32_e32 v50, v50, v50
	v_min_f32_e32 v50, 0x42700000, v50
	v_exp_f32_e32 v100, v50
	s_nop 0
	v_add_f32_e32 v50, 1.0, v100
	v_max_f32_e32 v34, v34, v34
	v_min_f32_e32 v34, 0x42700000, v34
	v_rcp_f32_e32 v101, v50
	v_exp_f32_e32 v34, v34
	v_max_f32_e32 v35, v35, v35
	v_min_f32_e32 v35, 0x42700000, v35
	v_mul_f32_e32 v98, v100, v101
	v_add_f32_e32 v100, 1.0, v34
	v_rcp_f32_e32 v100, v100
	v_cndmask_b32_e32 v50, 1.0, v101, vcc
	v_subrev_u32_e32 v101, 31, v90
	v_cndmask_b32_e32 v98, 0, v98, vcc
	v_cmp_lt_i32_e32 vcc, v101, v86
	s_or_b64 vcc, s[8:9], vcc
	v_mul_f32_e32 v34, v34, v100
	v_cndmask_b32_e32 v101, 1.0, v100, vcc
	v_cndmask_b32_e32 v100, 0, v34, vcc
	v_max_f32_e32 v34, v51, v51
	v_min_f32_e32 v34, 0x42700000, v34
	v_exp_f32_e32 v51, v34
	v_exp_f32_e32 v35, v35
	v_add_f32_e32 v34, 1.0, v51
	v_rcp_f32_e32 v102, v34
	v_subrev_u32_e32 v34, 62, v90
	v_cmp_lt_i32_e32 vcc, v34, v86
	s_or_b64 vcc, s[8:9], vcc
	v_mul_f32_e32 v51, v51, v102
	v_cndmask_b32_e32 v34, 1.0, v102, vcc
	v_cndmask_b32_e32 v102, 0, v51, vcc
	v_add_f32_e32 v51, 1.0, v35
	v_rcp_f32_e32 v51, v51
	v_cmp_lt_i32_e32 vcc, v103, v86
	s_or_b64 vcc, s[8:9], vcc
	v_mul_f32_e32 v35, v35, v51
	v_cndmask_b32_e32 v104, 0, v35, vcc
	v_max_f32_e32 v35, v52, v52
	v_min_f32_e32 v35, 0x42700000, v35
	v_exp_f32_e32 v35, v35
	v_cndmask_b32_e32 v103, 1.0, v51, vcc
	v_subrev_u32_e32 v52, 61, v90
	v_cmp_lt_i32_e32 vcc, v52, v86
	v_add_f32_e32 v51, 1.0, v35
	v_rcp_f32_e32 v51, v51
	s_or_b64 vcc, s[8:9], vcc
	v_mul_f32_e32 v35, v35, v51
	v_cndmask_b32_e32 v105, 0, v35, vcc
	v_max_f32_e32 v35, v36, v36
	v_min_f32_e32 v35, 0x42700000, v35
	v_exp_f32_e32 v35, v35
	v_cndmask_b32_e32 v52, 1.0, v51, vcc
	v_subrev_u32_e32 v51, 29, v90
	v_cmp_lt_i32_e32 vcc, v51, v86
	v_add_f32_e32 v36, 1.0, v35
	v_rcp_f32_e32 v36, v36
	s_or_b64 vcc, s[8:9], vcc
	v_mul_f32_e32 v35, v35, v36
	v_cndmask_b32_e32 v108, 0, v35, vcc
	v_max_f32_e32 v35, v53, v53
	v_min_f32_e32 v35, 0x42700000, v35
	v_exp_f32_e32 v35, v35
	v_cndmask_b32_e32 v107, 1.0, v36, vcc
	v_add_f32_e32 v36, 1.0, v35
	v_rcp_f32_e32 v51, v36
	v_subrev_u32_e32 v36, 60, v90
	v_cmp_lt_i32_e32 vcc, v36, v86
	s_or_b64 vcc, s[8:9], vcc
	v_mul_f32_e32 v35, v35, v51
	v_cndmask_b32_e32 v109, 0, v35, vcc
	v_max_f32_e32 v35, v37, v37
	v_min_f32_e32 v35, 0x42700000, v35
	v_exp_f32_e32 v35, v35
	v_cndmask_b32_e32 v36, 1.0, v51, vcc
	v_subrev_u32_e32 v51, 28, v90
	v_cmp_lt_i32_e32 vcc, v51, v86
	v_add_f32_e32 v37, 1.0, v35
	v_rcp_f32_e32 v37, v37
	s_or_b64 vcc, s[8:9], vcc
	v_subrev_u32_e32 v51, 55, v90
	v_mul_f32_e32 v35, v35, v37
	v_cndmask_b32_e32 v111, 0, v35, vcc
	v_max_f32_e32 v35, v54, v54
	v_min_f32_e32 v35, 0x42700000, v35
	v_exp_f32_e32 v35, v35
	v_cndmask_b32_e32 v110, 1.0, v37, vcc
	v_cmp_lt_i32_e32 vcc, v51, v86
	s_or_b64 vcc, s[8:9], vcc
	v_add_f32_e32 v37, 1.0, v35
	v_rcp_f32_e32 v37, v37
	s_nop 0
	v_mul_f32_e32 v35, v35, v37
	v_cndmask_b32_e32 v54, 0, v35, vcc
	v_max_f32_e32 v35, v38, v38
	v_min_f32_e32 v35, 0x42700000, v35
	v_exp_f32_e32 v35, v35
	v_cndmask_b32_e32 v51, 1.0, v37, vcc
	v_subrev_u32_e32 v38, 23, v90
	v_cmp_lt_i32_e32 vcc, v38, v86
	v_add_f32_e32 v37, 1.0, v35
	v_rcp_f32_e32 v37, v37
	s_or_b64 vcc, s[8:9], vcc
	v_subrev_u32_e32 v38, 54, v90
	v_mul_f32_e32 v35, v35, v37
	v_cndmask_b32_e32 v112, 0, v35, vcc
	v_max_f32_e32 v35, v55, v55
	v_min_f32_e32 v35, 0x42700000, v35
	v_exp_f32_e32 v35, v35
; DI float fast_exp2(float x) { return __builtin_amdgcn_exp2f(x); }
; DI float fast_rcp(float x) { return __builtin_amdgcn_rcpf(x); }
; DI void sb_wg_unit(bf16_t* act, int b, int hh, int Qb, LAS unsigned char* lds, volatile LAS unsigned* ctl, int tid, int wid, int lane) {
;     ...
;             for (int i = 0; i < 16; ++i) {
;                 const int kl = (i & 3) + 8 * (i >> 2) + 4 * h;
;                 { const float e = fast_exp2(fminf(p0[i], 60.f)); const float f = fast_rcp(1.f + e);
;                   const bool valid = !diag || (kv0 + kl < qpos); F0[i] = valid ? f : 1.f; p0[i] = valid ? e * f : 0.f; }
;                 { const float e = fast_exp2(fminf(p1[i], 60.f)); const float f = fast_rcp(1.f + e);
;                   const bool valid = !diag || (kv0 + 32 + kl < qpos); F1[i] = valid ? f : 1.f; p1[i] = valid ? e * f : 0.f; }
;             }
	v_cndmask_b32_e32 v53, 1.0, v37, vcc
	v_cmp_lt_i32_e32 vcc, v38, v86
	s_or_b64 vcc, s[8:9], vcc
	v_add_f32_e32 v37, 1.0, v35
	v_rcp_f32_e32 v37, v37
	v_subrev_u32_e32 v38, 22, v90
	v_mul_f32_e32 v35, v35, v37
	v_cndmask_b32_e32 v113, 0, v35, vcc
	v_max_f32_e32 v35, v39, v39
	v_min_f32_e32 v35, 0x42700000, v35
	v_exp_f32_e32 v35, v35
	v_cndmask_b32_e32 v55, 1.0, v37, vcc
	v_cmp_lt_i32_e32 vcc, v38, v86
	s_or_b64 vcc, s[8:9], vcc
	v_add_f32_e32 v37, 1.0, v35
	v_rcp_f32_e32 v37, v37
	v_subrev_u32_e32 v38, 53, v90
	v_mul_f32_e32 v35, v35, v37
	v_cndmask_b32_e32 v115, 0, v35, vcc
	v_max_f32_e32 v35, v56, v56
	v_min_f32_e32 v35, 0x42700000, v35
	v_exp_f32_e32 v35, v35
	v_cndmask_b32_e32 v114, 1.0, v37, vcc
	v_cmp_lt_i32_e32 vcc, v38, v86
	s_or_b64 vcc, s[8:9], vcc
	v_add_f32_e32 v37, 1.0, v35
	v_rcp_f32_e32 v37, v37
	v_subrev_u32_e32 v38, 21, v90
	v_mul_f32_e32 v35, v35, v37
	v_cndmask_b32_e32 v117, 0, v35, vcc
	v_max_f32_e32 v35, v40, v40
	v_min_f32_e32 v35, 0x42700000, v35
	v_exp_f32_e32 v35, v35
	v_cndmask_b32_e32 v116, 1.0, v37, vcc
	v_cmp_lt_i32_e32 vcc, v38, v86
	s_or_b64 vcc, s[8:9], vcc
	v_add_f32_e32 v37, 1.0, v35
	v_rcp_f32_e32 v37, v37
	v_subrev_u32_e32 v38, 52, v90
	v_mul_f32_e32 v35, v35, v37
	v_cndmask_b32_e32 v119, 0, v35, vcc
	v_max_f32_e32 v35, v57, v57
	v_min_f32_e32 v35, 0x42700000, v35
	v_exp_f32_e32 v35, v35
	v_cndmask_b32_e32 v118, 1.0, v37, vcc
	v_cmp_lt_i32_e32 vcc, v38, v86
	s_or_b64 vcc, s[8:9], vcc
	v_add_f32_e32 v37, 1.0, v35
	v_rcp_f32_e32 v37, v37
	v_subrev_u32_e32 v38, 20, v90
	v_mul_f32_e32 v35, v35, v37
	v_cndmask_b32_e32 v121, 0, v35, vcc
	v_max_f32_e32 v35, v41, v41
	v_min_f32_e32 v35, 0x42700000, v35
	v_exp_f32_e32 v35, v35
	v_cndmask_b32_e32 v120, 1.0, v37, vcc
	v_cmp_lt_i32_e32 vcc, v38, v86
	s_or_b64 vcc, s[8:9], vcc
	v_add_f32_e32 v37, 1.0, v35
	v_rcp_f32_e32 v37, v37
	v_subrev_u32_e32 v38, 47, v90
	v_subrev_u32_e32 v41, 45, v90
	v_mul_f32_e32 v35, v35, v37
	v_cndmask_b32_e32 v123, 0, v35, vcc
	v_max_f32_e32 v35, v58, v58
	v_min_f32_e32 v35, 0x42700000, v35
	v_exp_f32_e32 v35, v35
	v_cndmask_b32_e32 v122, 1.0, v37, vcc
	v_cmp_lt_i32_e32 vcc, v38, v86
	s_or_b64 vcc, s[8:9], vcc
	v_add_f32_e32 v37, 1.0, v35
	v_rcp_f32_e32 v37, v37
	v_add_u32_e32 v38, -15, v90
	v_mul_f32_e32 v35, v35, v37
	v_cndmask_b32_e32 v124, 0, v35, vcc
	v_max_f32_e32 v35, v42, v42
	v_min_f32_e32 v35, 0x42700000, v35
	v_exp_f32_e32 v35, v35
	v_cndmask_b32_e32 v39, 1.0, v37, vcc
	v_cmp_lt_i32_e32 vcc, v38, v86
	s_or_b64 vcc, s[8:9], vcc
	v_add_f32_e32 v37, 1.0, v35
	v_rcp_f32_e32 v37, v37
	v_subrev_u32_e32 v38, 46, v90
	v_mul_f32_e32 v35, v35, v37
	v_cndmask_b32_e32 v125, 0, v35, vcc
	v_max_f32_e32 v35, v59, v59
	v_min_f32_e32 v35, 0x42700000, v35
	v_exp_f32_e32 v35, v35
	v_cndmask_b32_e32 v40, 1.0, v37, vcc
	v_cmp_lt_i32_e32 vcc, v38, v86
	s_or_b64 vcc, s[8:9], vcc
	v_add_f32_e32 v37, 1.0, v35
	v_rcp_f32_e32 v37, v37
	v_add_u32_e32 v38, -14, v90
	v_mul_f32_e32 v35, v35, v37
	v_cndmask_b32_e32 v127, 0, v35, vcc
	v_max_f32_e32 v35, v43, v43
	v_min_f32_e32 v35, 0x42700000, v35
	v_exp_f32_e32 v35, v35
	v_cndmask_b32_e32 v126, 1.0, v37, vcc
	v_cmp_lt_i32_e32 vcc, v38, v86
	s_or_b64 vcc, s[8:9], vcc
	v_add_f32_e32 v37, 1.0, v35
	v_rcp_f32_e32 v37, v37
	v_subrev_u32_e32 v43, 38, v90
	v_mul_f32_e32 v35, v35, v37
	v_cndmask_b32_e32 v128, 0, v35, vcc
	v_max_f32_e32 v35, v60, v60
	v_min_f32_e32 v35, 0x42700000, v35
	v_exp_f32_e32 v35, v35
	v_cndmask_b32_e32 v38, 1.0, v37, vcc
	v_cmp_lt_i32_e32 vcc, v41, v86
	s_or_b64 vcc, s[8:9], vcc
	v_add_f32_e32 v37, 1.0, v35
	v_rcp_f32_e32 v37, v37
	v_add_u32_e32 v41, -13, v90
	v_mul_f32_e32 v35, v35, v37
	v_cndmask_b32_e32 v130, 0, v35, vcc
	v_max_f32_e32 v35, v44, v44
	v_min_f32_e32 v35, 0x42700000, v35
	v_exp_f32_e32 v35, v35
	v_cndmask_b32_e32 v129, 1.0, v37, vcc
	v_cmp_lt_i32_e32 vcc, v41, v86
	s_or_b64 vcc, s[8:9], vcc
	v_add_f32_e32 v37, 1.0, v35
	v_rcp_f32_e32 v37, v37
	v_subrev_u32_e32 v41, 44, v90
	v_mul_f32_e32 v35, v35, v37
	v_cndmask_b32_e32 v132, 0, v35, vcc
	v_max_f32_e32 v35, v61, v61
	v_min_f32_e32 v35, 0x42700000, v35
	v_exp_f32_e32 v35, v35
	v_cndmask_b32_e32 v131, 1.0, v37, vcc
	v_cmp_lt_i32_e32 vcc, v41, v86
	s_or_b64 vcc, s[8:9], vcc
	v_add_f32_e32 v37, 1.0, v35
	v_rcp_f32_e32 v37, v37
	v_add_u32_e32 v41, -12, v90
	v_mul_f32_e32 v35, v35, v37
	v_cndmask_b32_e32 v134, 0, v35, vcc
	v_max_f32_e32 v35, v45, v45
	v_min_f32_e32 v35, 0x42700000, v35
	v_exp_f32_e32 v35, v35
	v_cndmask_b32_e32 v133, 1.0, v37, vcc
	v_cmp_lt_i32_e32 vcc, v41, v86
	s_or_b64 vcc, s[8:9], vcc
	v_add_f32_e32 v37, 1.0, v35
	v_rcp_f32_e32 v37, v37
	v_subrev_u32_e32 v41, 39, v90
	v_mul_f32_e32 v35, v35, v37
	v_cndmask_b32_e32 v136, 0, v35, vcc
	v_max_f32_e32 v35, v62, v62
	v_min_f32_e32 v35, 0x42700000, v35
	v_exp_f32_e32 v35, v35
	v_cndmask_b32_e32 v135, 1.0, v37, vcc
	v_cmp_lt_i32_e32 vcc, v41, v86
	s_or_b64 vcc, s[8:9], vcc
	v_add_f32_e32 v37, 1.0, v35
	v_rcp_f32_e32 v37, v37
	v_add_u32_e32 v41, -7, v90
	v_mul_f32_e32 v44, v131, v135
	v_mul_f32_e32 v35, v35, v37
	v_cndmask_b32_e32 v137, 0, v35, vcc
	v_max_f32_e32 v35, v46, v46
	v_min_f32_e32 v35, 0x42700000, v35
	v_exp_f32_e32 v35, v35
	v_cndmask_b32_e32 v42, 1.0, v37, vcc
	v_cmp_lt_i32_e32 vcc, v41, v86
	s_or_b64 vcc, s[8:9], vcc
	v_add_f32_e32 v37, 1.0, v35
	v_rcp_f32_e32 v37, v37
	s_nop 0
	v_mul_f32_e32 v35, v35, v37
	v_cndmask_b32_e32 v138, 0, v35, vcc
	v_max_f32_e32 v35, v63, v63
	v_min_f32_e32 v35, 0x42700000, v35
	v_exp_f32_e32 v35, v35
	v_cndmask_b32_e32 v41, 1.0, v37, vcc
	v_cmp_lt_i32_e32 vcc, v43, v86
	s_or_b64 vcc, s[8:9], vcc
	v_add_f32_e32 v37, 1.0, v35
	v_rcp_f32_e32 v37, v37
	v_add_u32_e32 v43, -6, v90
	v_mul_f32_e32 v35, v35, v37
; DI float xhalf_other(float v) { const unsigned b = __float_as_uint(v); auto rr = __builtin_amdgcn_permlane32_swap(b, b, false, false); return __uint_as_float(rr[0] ^ rr[1] ^ b); }
; DI void sb_wg_unit(bf16_t* act, int b, int hh, int Qb, LAS unsigned char* lds, volatile LAS unsigned* ctl, int tid, int wid, int lane) {
;     ...
;             float G[8], Go[8];
; #pragma unroll
;             for (int g = 0; g < 4; ++g) { G[g] = (F0[4 * g] * F0[4 * g + 1]) * (F0[4 * g + 2] * F0[4 * g + 3]); G[4 + g] = (F1[4 * g] * F1[4 * g + 1]) * (F1[4 * g + 2] * F1[4 * g + 3]); }
; #pragma unroll
;             for (int g = 0; g < 8; ++g) Go[g] = xhalf_other(G[g]);
;             float run = C; float A[8];
; #pragma unroll
;             for (int g = 7; g >= 0; --g) { A[g] = run * (h == 0 ? Go[g] : 1.f); run *= (G[g] * Go[g]); }
; #pragma unroll
;             for (int g = 0; g < 4; ++g) {
;                 { float bt = A[g]; p0[4 * g + 3] *= bt; bt *= F0[4 * g + 3]; p0[4 * g + 2] *= bt; bt *= F0[4 * g + 2]; p0[4 * g + 1] *= bt; bt *= F0[4 * g + 1]; p0[4 * g] *= bt; }
;                 { float bt = A[4 + g]; p1[4 * g + 3] *= bt; bt *= F1[4 * g + 3]; p1[4 * g + 2] *= bt; bt *= F1[4 * g + 2]; p1[4 * g + 1] *= bt; bt *= F1[4 * g + 1]; p1[4 * g] *= bt; }
;             }
;             C = run;
;             pv_tile(o0, o1, Vs, p0, p1, lane);
	v_cndmask_b32_e32 v139, 0, v35, vcc
	v_max_f32_e32 v35, v47, v47
	v_min_f32_e32 v35, 0x42700000, v35
	v_exp_f32_e32 v35, v35
	v_cndmask_b32_e32 v56, 1.0, v37, vcc
	v_cmp_lt_i32_e32 vcc, v43, v86
	s_or_b64 vcc, s[8:9], vcc
	v_add_f32_e32 v37, 1.0, v35
	v_rcp_f32_e32 v37, v37
	v_subrev_u32_e32 v43, 37, v90
	v_mul_f32_e32 v35, v35, v37
	v_cndmask_b32_e32 v141, 0, v35, vcc
	v_max_f32_e32 v35, v64, v64
	v_min_f32_e32 v35, 0x42700000, v35
	v_exp_f32_e32 v35, v35
	v_cndmask_b32_e32 v140, 1.0, v37, vcc
	v_cmp_lt_i32_e32 vcc, v43, v86
	s_or_b64 vcc, s[8:9], vcc
	v_add_f32_e32 v37, 1.0, v35
	v_rcp_f32_e32 v37, v37
	v_add_u32_e32 v43, -5, v90
	v_mul_f32_e32 v41, v41, v140
	v_mul_f32_e32 v35, v35, v37
	v_cndmask_b32_e32 v63, 0, v35, vcc
	v_max_f32_e32 v35, v48, v48
	v_min_f32_e32 v35, 0x42700000, v35
	v_exp_f32_e32 v35, v35
	v_cndmask_b32_e32 v58, 1.0, v37, vcc
	v_cmp_lt_i32_e32 vcc, v43, v86
	s_or_b64 vcc, s[8:9], vcc
	v_add_f32_e32 v37, 1.0, v35
	v_rcp_f32_e32 v37, v37
	v_subrev_u32_e32 v43, 36, v90
	v_mul_f32_e32 v35, v35, v37
	v_cndmask_b32_e32 v143, 0, v35, vcc
	v_max_f32_e32 v35, v65, v65
	v_min_f32_e32 v35, 0x42700000, v35
	v_exp_f32_e32 v35, v35
	v_cndmask_b32_e32 v142, 1.0, v37, vcc
	v_cmp_lt_i32_e32 vcc, v43, v86
	s_or_b64 vcc, s[8:9], vcc
	v_add_f32_e32 v37, 1.0, v35
	v_rcp_f32_e32 v37, v37
	v_add_u32_e32 v43, -4, v90
	v_mul_f32_e32 v35, v35, v37
	v_cndmask_b32_e32 v62, 0, v35, vcc
	v_max_f32_e32 v35, v49, v49
	v_min_f32_e32 v35, 0x42700000, v35
	v_exp_f32_e32 v35, v35
	v_cndmask_b32_e32 v60, 1.0, v37, vcc
	v_cmp_lt_i32_e32 vcc, v43, v86
	s_or_b64 vcc, s[8:9], vcc
	v_add_f32_e32 v37, 1.0, v35
	v_rcp_f32_e32 v37, v37
	s_mov_b32 s8, 0x800000
	v_mul_f32_e32 v35, v35, v37
	v_cndmask_b32_e32 v144, 1.0, v37, vcc
	v_cndmask_b32_e32 v145, 0, v35, vcc
	v_mul_f32_e32 v35, v101, v103
	v_mul_f32_e32 v37, v107, v110
	v_mul_f32_e32 v43, v35, v37
	v_mul_f32_e32 v35, v51, v55
	v_mul_f32_e32 v37, v116, v120
	v_mul_f32_e32 v51, v35, v37
	v_mul_f32_e32 v35, v53, v114
	v_mul_f32_e32 v37, v118, v122
	v_mul_f32_e32 v37, v35, v37
	v_mul_f32_e32 v35, v39, v126
	v_mul_f32_e32 v39, v129, v133
	v_mul_f32_e32 v46, v35, v39
	v_mov_b32_e32 v35, v51
	v_mov_b32_e32 v45, v51
	s_nop 1
	v_permlane32_swap_b32_e32 v35, v45
	v_xor_b32_e32 v35, v35, v45
	v_mov_b32_e32 v45, v46
	v_mov_b32_e32 v47, v46
	s_nop 1
	v_permlane32_swap_b32_e32 v45, v47
	v_xor_b32_e32 v45, v45, v47
	v_xor_b32_e32 v47, v45, v46
	v_mov_b32_e32 v45, v43
	v_mov_b32_e32 v48, v43
	s_nop 1
	v_permlane32_swap_b32_e32 v45, v48
	v_xor_b32_e32 v45, v45, v48
	v_xor_b32_e32 v57, v45, v43
	v_mov_b32_e32 v45, v37
	v_mov_b32_e32 v48, v37
	v_mul_f32_e32 v39, v142, v144
	s_nop 0
	v_permlane32_swap_b32_e32 v45, v48
	v_xor_b32_e32 v45, v45, v48
	v_pk_mul_f32 v[40:41], v[40:41], v[38:39]
	v_xor_b32_e32 v48, v45, v37
	v_mov_b32_e32 v39, v41
	v_mov_b32_e32 v45, v41
	s_nop 1
	v_permlane32_swap_b32_e32 v39, v45
	v_xor_b32_e32 v39, v39, v45
	v_xor_b32_e32 v45, v39, v41
	v_pk_mul_f32 v[40:41], v[40:41], v[44:45]
	v_mul_f32_e32 v59, v37, v48
	v_mov_b32_e32 v39, v40
	v_mov_b32_e32 v44, v40
	s_nop 1
	v_permlane32_swap_b32_e32 v39, v44
	v_xor_b32_e32 v39, v39, v44
	v_xor_b32_e32 v90, v39, v40
	v_cndmask_b32_e64 v39, 1.0, v45, s[42:43]
	v_mul_f32_e32 v101, v91, v39
	v_cndmask_b32_e64 v39, 1.0, v90, s[42:43]
	v_pk_mul_f32 v[40:41], v[40:41], v[90:91]
	v_pk_mul_f32 v[42:43], v[42:43], v[56:57]
	v_mul_f32_e32 v49, v39, v41
	v_pk_mul_f32 v[40:41], v[40:41], v[40:41] op_sel:[0,1] op_sel_hi:[1,0]
	v_cndmask_b32_e64 v39, 1.0, v48, s[42:43]
	v_mov_b32_e32 v61, v40
	v_mul_f32_e32 v45, v39, v40
	v_pk_mul_f32 v[40:41], v[58:59], v[60:61]
	v_cndmask_b32_e64 v37, 1.0, v57, s[42:43]
	v_pk_mul_f32 v[42:43], v[42:43], v[40:41]
	v_mul_f32_e32 v48, v37, v41
	v_mov_b32_e32 v39, v42
	v_mov_b32_e32 v40, v42
	s_nop 1
	v_permlane32_swap_b32_e32 v39, v40
	v_xor_b32_e32 v39, v39, v40
	v_xor_b32_e32 v39, v39, v42
	v_cndmask_b32_e64 v37, 1.0, v39, s[42:43]
	v_mul_f32_e32 v64, v37, v43
	v_mul_f32_e32 v37, v42, v39
	v_xor_b32_e32 v35, v35, v51
	v_mul_f32_e32 v37, v37, v43
	v_mul_f32_e32 v53, v46, v47
	v_pk_mul_f32 v[40:41], v[52:53], v[36:37]
	v_pk_mul_f32 v[42:43], v[50:51], v[34:35]
	v_cndmask_b32_e64 v39, 1.0, v47, s[42:43]
	v_pk_mul_f32 v[42:43], v[42:43], v[40:41]
	v_mul_f32_e32 v57, v39, v37
	v_cndmask_b32_e64 v39, 1.0, v35, s[42:43]
	v_mov_b32_e32 v35, v42
	v_mov_b32_e32 v37, v42
	s_nop 1
	v_permlane32_swap_b32_e32 v35, v37
	v_xor_b32_e32 v35, v35, v37
	v_xor_b32_e32 v35, v35, v42
	v_mul_f32_e32 v39, v39, v41
	v_cndmask_b32_e64 v37, 1.0, v35, s[42:43]
	v_mul_f32_e32 v37, v37, v43
	v_mul_f32_e32 v35, v42, v35
	v_mul_f32_e32 v50, v121, v39
	v_mul_f32_e32 v39, v120, v39
	v_mul_f32_e32 v91, v35, v43
	v_mul_f32_e32 v35, v36, v37
	v_mul_f32_e32 v51, v117, v39
	v_mul_f32_e32 v39, v116, v39
	v_mul_f32_e32 v42, v105, v35
	v_mul_f32_e32 v35, v52, v35
	v_mul_f32_e32 v52, v113, v39
	v_mul_f32_e32 v39, v55, v39
	v_mul_f32_e32 v43, v122, v45
	v_mul_f32_e32 v55, v54, v39
	v_mul_f32_e32 v39, v123, v45
	v_mul_f32_e32 v45, v118, v43
	v_mul_f32_e32 v41, v119, v43
	v_mul_f32_e32 v43, v115, v45
	v_mul_f32_e32 v45, v114, v45
	v_mul_f32_e32 v46, v112, v45
	v_mul_f32_e32 v45, v133, v57
	v_mul_f32_e32 v54, v134, v57
	v_mul_f32_e32 v57, v130, v45
	v_mul_f32_e32 v45, v129, v45
	v_mul_f32_e32 v59, v127, v45
	v_mul_f32_e32 v45, v126, v45
	v_mul_f32_e32 v34, v34, v35
	v_mul_f32_e32 v36, v110, v48
	v_mul_f32_e32 v61, v124, v45
	v_mul_f32_e32 v45, v136, v49
	v_mul_f32_e32 v49, v135, v49
	v_add_u32_e32 v90, s13, v87
	v_mul_f32_e32 v40, v109, v37
	v_mul_f32_e32 v44, v102, v35
	v_mul_f32_e32 v47, v98, v34
	v_mul_f32_e32 v34, v111, v48
	v_mul_f32_e32 v35, v108, v36
	v_mul_f32_e32 v53, v131, v49
	ds_read_b64_tr_b16 v[108:109], v90 offset:8192
	ds_read_b64_tr_b16 v[110:111], v90 offset:8704
	ds_read_b64_tr_b16 v[112:113], v90 offset:12288
	ds_read_b64_tr_b16 v[114:115], v90 offset:12800
	v_mul_f32_e32 v48, v132, v49
	v_mul_f32_e32 v49, v128, v53
	v_mul_f32_e32 v38, v38, v53
	v_mul_f32_e32 v53, v60, v64
	v_mul_f32_e32 v37, v107, v36
	v_mul_f32_e32 v63, v63, v53
	v_mul_f32_e32 v53, v58, v53
	v_mul_f32_e32 v36, v104, v37
	v_mul_f32_e32 v37, v103, v37
	v_mul_f32_e32 v62, v62, v64
	v_mul_f32_e32 v64, v139, v53
	v_mul_f32_e32 v53, v56, v53
	v_mul_f32_e32 v37, v100, v37
	v_mul_f32_e32 v65, v137, v53
	v_mul_f32_e32 v53, v145, v101
	v_mul_f32_e32 v58, v144, v101
	v_cvt_pk_bf16_f32 v100, v47, v44
	v_cvt_pk_bf16_f32 v101, v42, v40
	v_cvt_pk_bf16_f32 v102, v55, v52
	v_cvt_pk_bf16_f32 v103, v51, v50
	v_mul_f32_e32 v38, v125, v38
	v_mul_f32_e32 v60, v142, v58
	s_waitcnt lgkmcnt(2)
; #define LAS __attribute__((address_space(3)))
; #define MFMA32(a, b, c) __builtin_amdgcn_mfma_f32_32x32x16_bf16((a), (b), (c), 0, 0, 0)
; DI s16x4 vtr(LAS const unsigned char* p) { return __builtin_bit_cast(s16x4, __builtin_amdgcn_ds_read_tr16_b64_v4i16((LAS v4i16_t*)p)); }
; DI void pv_tile(f32x16& o0, f32x16& o1, LAS const unsigned char* Vs, const f32x16& p0, const f32x16& p1, int lane) {
;     const int h = lane >> 5;
;     LAS const unsigned char* vb = Vs + (4 * h + ((lane & 15) >> 2)) * 64 + ((lane >> 4) & 1) * 32 + (lane & 3) * 8;
; #pragma unroll
;     for (int kh = 0; kh < 2; ++kh)
; #pragma unroll
;         for (int s2 = 0; s2 < 2; ++s2) {
;             const bf16x8 pb = kh ? pack8(p1, s2) : pack8(p0, s2);
;             const int ro = (32 * kh + 16 * s2) * 64;
;             const s16x4 l0 = vtr(vb + ro), h0 = vtr(vb + ro + 512), l1 = vtr(vb + 4096 + ro), h1 = vtr(vb + 4096 + ro + 512);
;             const bf16x8 v0 = (bf16x8){l0[0], l0[1], l0[2], l0[3], h0[0], h0[1], h0[2], h0[3]};
;             const bf16x8 v1 = (bf16x8){l1[0], l1[1], l1[2], l1[3], h1[0], h1[1], h1[2], h1[3]};
;             o0 = MFMA32(v0, pb, o0); o1 = MFMA32(v1, pb, o1);
;         }
; }
; DI void sb_wg_unit(bf16_t* act, int b, int hh, int Qb, LAS unsigned char* lds, volatile LAS unsigned* ctl, int tid, int wid, int lane) {
;     ...
;             pv_tile(o0, o1, Vs, p0, p1, lane);
;             if (__all(C < 1.17549435e-38f)) done = true;
;             --t;
;         }
	v_mfma_f32_32x32x16_bf16 v[18:33], v[108:111], v[100:103], v[18:33]
	v_mul_f32_e32 v56, v143, v58
	v_mul_f32_e32 v58, v141, v60
	v_mul_f32_e32 v60, v140, v60
	v_mul_f32_e32 v60, v138, v60
	v_cmp_gt_f32_e32 vcc, s8, v91
	s_cmp_eq_u64 vcc, exec
	s_cselect_b64 s[8:9], -1, 0
	s_waitcnt lgkmcnt(0)
	v_mfma_f32_32x32x16_bf16 v[2:17], v[112:115], v[100:103], v[2:17]
	v_cvt_pk_bf16_f32 v102, v65, v64
	v_cvt_pk_bf16_f32 v103, v63, v62
	ds_read_b64_tr_b16 v[62:63], v90 offset:9216
	ds_read_b64_tr_b16 v[64:65], v90 offset:9728
	ds_read_b64_tr_b16 v[108:109], v90 offset:13312
	ds_read_b64_tr_b16 v[110:111], v90 offset:13824
	v_cvt_pk_bf16_f32 v100, v61, v59
	v_cvt_pk_bf16_f32 v101, v57, v54
	s_add_i32 s24, s24, -1
	s_cmp_le_i32 s10, s23
	s_waitcnt lgkmcnt(2)
	v_mfma_f32_32x32x16_bf16 v[18:33], v[62:65], v[100:103], v[18:33]
	v_cvt_pk_bf16_f32 v62, v37, v36
	v_cvt_pk_bf16_f32 v63, v35, v34
	v_cvt_pk_bf16_f32 v64, v46, v43
	v_cvt_pk_bf16_f32 v65, v41, v39
	ds_read_b64_tr_b16 v[34:35], v90 offset:10240
	ds_read_b64_tr_b16 v[36:37], v90 offset:10752
	ds_read_b64_tr_b16 v[40:41], v90 offset:14336
	ds_read_b64_tr_b16 v[42:43], v90 offset:14848
	s_cselect_b64 s[10:11], -1, 0
	s_or_b64 s[10:11], s[8:9], s[10:11]
	s_waitcnt lgkmcnt(4)
	v_mfma_f32_32x32x16_bf16 v[2:17], v[108:111], v[100:103], v[2:17]
	s_sub_i32 s12, s12, 64
	v_add_u32_e32 v87, 0x4000, v87
	s_andn2_b64 vcc, exec, s[10:11]
	s_waitcnt lgkmcnt(2)
	v_mfma_f32_32x32x16_bf16 v[18:33], v[34:37], v[62:65], v[18:33]
	v_cvt_pk_bf16_f32 v34, v38, v49
	v_cvt_pk_bf16_f32 v35, v48, v45
	v_cvt_pk_bf16_f32 v36, v60, v58
	v_cvt_pk_bf16_f32 v37, v56, v53
	s_waitcnt lgkmcnt(0)
	v_mfma_f32_32x32x16_bf16 v[2:17], v[40:43], v[62:65], v[2:17]
	ds_read_b64_tr_b16 v[38:39], v90 offset:11264
	ds_read_b64_tr_b16 v[40:41], v90 offset:11776
	ds_read_b64_tr_b16 v[42:43], v90 offset:15360
	ds_read_b64_tr_b16 v[44:45], v90 offset:15872
	s_waitcnt lgkmcnt(2)
	v_mfma_f32_32x32x16_bf16 v[18:33], v[38:41], v[34:37], v[18:33]
	s_waitcnt lgkmcnt(0)
	v_mfma_f32_32x32x16_bf16 v[2:17], v[42:45], v[34:37], v[2:17]
	s_cbranch_vccnz .LBB0_355

; DI unsigned cvtpk(float lo, float hi) { typedef float f2 __attribute__((ext_vector_type(2))); typedef __bf16 b2 __attribute__((ext_vector_type(2))); f2 v = {lo, hi}; b2 b = __builtin_convertvector(v, b2); return __builtin_bit_cast(unsigned, b); }
; DI float bflo(unsigned w) { return __uint_as_float(w << 16); }
; DI float bfhi(unsigned w) { return __uint_as_float(w & 0xffff0000u); }
; DI float fast_rcp(float x) { return __builtin_amdgcn_rcpf(x); }
; DI float xhalf_sum(float v) { auto rr = __builtin_amdgcn_permlane32_swap(__float_as_uint(v), __float_as_uint(v), false, false); return __uint_as_float(rr[0]) + __uint_as_float(rr[1]); }
; DI float silu_(float g) { return g * fast_rcp(1.f + fast_exp2(-g * LOG2E)); }
; DI void write_y(const f32x16& o0, const f32x16& o1, float scale, const bf16_t* grow, bf16_t* yrow, int h) {
; #pragma unroll
;     for (int dh = 0; dh < 2; ++dh) {
;         u32x2 w[4];
; #pragma unroll
;         for (int grp = 0; grp < 4; ++grp) {
;             const int d0 = 32 * dh + 8 * grp + 4 * h;
;             const u32x2 g = *(const u32x2*)(grow + d0);
;             const f32x16& o = dh ? o1 : o0;
;             const float y0 = o[4 * grp + 0] * scale * silu_(bflo(g.x)), y1 = o[4 * grp + 1] * scale * silu_(bfhi(g.x));
;             const float y2 = o[4 * grp + 2] * scale * silu_(bflo(g.y)), y3 = o[4 * grp + 3] * scale * silu_(bfhi(g.y));
;             w[grp].x = cvtpk(y0, y1); w[grp].y = cvtpk(y2, y3);
;         }
;         store_pair16(yrow + 32 * dh, w[0], w[1], 0, h);
;         store_pair16(yrow + 32 * dh, w[2], w[3], 1, h);
;     }
; }
; DI void swa_wg_unit(bf16_t* act, int b, int hk, int Qb, const float* sinks_l, LAS const float* tabS, LAS unsigned char* lds, int wid, int lane) {
;     ...
;         l = xhalf_sum(l);
;         write_y(o0, o1, fast_rcp(l), act + rowq * PITCH + C_GC + hq * 64, act + rowq * PITCH + C_QC + hq * 64, h);
.LBB0_377:
	s_lshl_b32 s10, s10, 6
	s_lshl_b32 s38, s10, 1
	v_mov_b32_e32 v0, v118
	s_nop 1
	v_permlane32_swap_b32_e32 v118, v0
	v_add_f32_e32 v0, v118, v0
	v_rcp_f32_e32 v0, v0
	s_add_i32 s13, s13, 1
	s_cmp_eq_u32 s13, 4
	s_waitcnt vmcnt(0)
	v_lshlrev_b32_e32 v64, 16, v160
	v_and_b32_e32 v65, 0xffff0000, v160
	v_lshlrev_b32_e32 v66, 16, v161
	v_and_b32_e32 v67, 0xffff0000, v161
	v_mul_f32_e32 v68, 0xbfb8aa3b, v64
	v_mul_f32_e32 v69, 0xbfb8aa3b, v65
	v_mul_f32_e32 v70, 0xbfb8aa3b, v66
	v_mul_f32_e32 v71, 0xbfb8aa3b, v67
	v_exp_f32_e32 v68, v68
	v_exp_f32_e32 v69, v69
	v_exp_f32_e32 v70, v70
	v_exp_f32_e32 v71, v71
	v_add_f32_e32 v68, 1.0, v68
	v_add_f32_e32 v69, 1.0, v69
	v_add_f32_e32 v70, 1.0, v70
	v_add_f32_e32 v71, 1.0, v71
	v_rcp_f32_e32 v68, v68
	v_rcp_f32_e32 v69, v69
	v_rcp_f32_e32 v70, v70
	v_rcp_f32_e32 v71, v71
	v_mul_f32_e32 v64, v68, v64
	v_mul_f32_e32 v65, v69, v65
	v_mul_f32_e32 v66, v70, v66
	v_mul_f32_e32 v67, v71, v67
	v_mul_f32_e32 v32, v32, v0
	v_mul_f32_e32 v33, v33, v0
	v_mul_f32_e32 v34, v34, v0
	v_mul_f32_e32 v35, v35, v0
	v_mul_f32_e32 v32, v32, v64
	v_mul_f32_e32 v33, v33, v65
	v_mul_f32_e32 v34, v34, v66
	v_mul_f32_e32 v35, v35, v67
	v_cvt_pk_bf16_f32 v32, v32, v33
	v_cvt_pk_bf16_f32 v33, v34, v35
	v_lshlrev_b32_e32 v64, 16, v162
	v_and_b32_e32 v65, 0xffff0000, v162
	v_lshlrev_b32_e32 v66, 16, v163
	v_and_b32_e32 v67, 0xffff0000, v163
	v_mul_f32_e32 v68, 0xbfb8aa3b, v64
	v_mul_f32_e32 v69, 0xbfb8aa3b, v65
	v_mul_f32_e32 v70, 0xbfb8aa3b, v66
	v_mul_f32_e32 v71, 0xbfb8aa3b, v67
	v_exp_f32_e32 v68, v68
	v_exp_f32_e32 v69, v69
	v_exp_f32_e32 v70, v70
	v_exp_f32_e32 v71, v71
	v_add_f32_e32 v68, 1.0, v68
	v_add_f32_e32 v69, 1.0, v69
	v_add_f32_e32 v70, 1.0, v70
	v_add_f32_e32 v71, 1.0, v71
	v_rcp_f32_e32 v68, v68
	v_rcp_f32_e32 v69, v69
	v_rcp_f32_e32 v70, v70
	v_rcp_f32_e32 v71, v71
	v_mul_f32_e32 v64, v68, v64
	v_mul_f32_e32 v65, v69, v65
	v_mul_f32_e32 v66, v70, v66
	v_mul_f32_e32 v67, v71, v67
	v_mul_f32_e32 v36, v36, v0
	v_mul_f32_e32 v37, v37, v0
	v_mul_f32_e32 v38, v38, v0
	v_mul_f32_e32 v39, v39, v0
	v_mul_f32_e32 v36, v36, v64
	v_mul_f32_e32 v37, v37, v65
	v_mul_f32_e32 v38, v38, v66
	v_mul_f32_e32 v39, v39, v67
	v_cvt_pk_bf16_f32 v34, v36, v37
	v_cvt_pk_bf16_f32 v35, v38, v39
	s_nop 1
	v_permlane32_swap_b32_e32 v32, v34
	v_permlane32_swap_b32_e32 v33, v35
	global_store_dwordx4 v[104:105], v[32:35], off
	v_lshlrev_b32_e32 v64, 16, v164
	v_and_b32_e32 v65, 0xffff0000, v164
	v_lshlrev_b32_e32 v66, 16, v165
	v_and_b32_e32 v67, 0xffff0000, v165
	v_mul_f32_e32 v68, 0xbfb8aa3b, v64
	v_mul_f32_e32 v69, 0xbfb8aa3b, v65
	v_mul_f32_e32 v70, 0xbfb8aa3b, v66
	v_mul_f32_e32 v71, 0xbfb8aa3b, v67
	v_exp_f32_e32 v68, v68
	v_exp_f32_e32 v69, v69
	v_exp_f32_e32 v70, v70
	v_exp_f32_e32 v71, v71
	v_add_f32_e32 v68, 1.0, v68
	v_add_f32_e32 v69, 1.0, v69
	v_add_f32_e32 v70, 1.0, v70
	v_add_f32_e32 v71, 1.0, v71
	v_rcp_f32_e32 v68, v68
	v_rcp_f32_e32 v69, v69
	v_rcp_f32_e32 v70, v70
	v_rcp_f32_e32 v71, v71
	v_mul_f32_e32 v64, v68, v64
	v_mul_f32_e32 v65, v69, v65
	v_mul_f32_e32 v66, v70, v66
	v_mul_f32_e32 v67, v71, v67
	v_mul_f32_e32 v40, v40, v0
	v_mul_f32_e32 v41, v41, v0
	v_mul_f32_e32 v42, v42, v0
	v_mul_f32_e32 v43, v43, v0
	v_mul_f32_e32 v40, v40, v64
	v_mul_f32_e32 v41, v41, v65
	v_mul_f32_e32 v42, v42, v66
	v_mul_f32_e32 v43, v43, v67
	v_cvt_pk_bf16_f32 v40, v40, v41
	v_cvt_pk_bf16_f32 v41, v42, v43
	v_lshlrev_b32_e32 v64, 16, v166
	v_and_b32_e32 v65, 0xffff0000, v166
	v_lshlrev_b32_e32 v66, 16, v167
	v_and_b32_e32 v67, 0xffff0000, v167
	v_mul_f32_e32 v68, 0xbfb8aa3b, v64
	v_mul_f32_e32 v69, 0xbfb8aa3b, v65
	v_mul_f32_e32 v70, 0xbfb8aa3b, v66
	v_mul_f32_e32 v71, 0xbfb8aa3b, v67
	v_exp_f32_e32 v68, v68
	v_exp_f32_e32 v69, v69
	v_exp_f32_e32 v70, v70
	v_exp_f32_e32 v71, v71
	v_add_f32_e32 v68, 1.0, v68
	v_add_f32_e32 v69, 1.0, v69
	v_add_f32_e32 v70, 1.0, v70
	v_add_f32_e32 v71, 1.0, v71
	v_rcp_f32_e32 v68, v68
	v_rcp_f32_e32 v69, v69
	v_rcp_f32_e32 v70, v70
	v_rcp_f32_e32 v71, v71
	v_mul_f32_e32 v64, v68, v64
	v_mul_f32_e32 v65, v69, v65
	v_mul_f32_e32 v66, v70, v66
	v_mul_f32_e32 v67, v71, v67
	v_mul_f32_e32 v44, v44, v0
	v_mul_f32_e32 v45, v45, v0
	v_mul_f32_e32 v46, v46, v0
	v_mul_f32_e32 v47, v47, v0
	v_mul_f32_e32 v44, v44, v64
	v_mul_f32_e32 v45, v45, v65
	v_mul_f32_e32 v46, v46, v66
	v_mul_f32_e32 v47, v47, v67
	v_cvt_pk_bf16_f32 v42, v44, v45
	v_cvt_pk_bf16_f32 v43, v46, v47
	s_nop 1
	v_permlane32_swap_b32_e32 v40, v42
	v_permlane32_swap_b32_e32 v41, v43
	global_store_dwordx4 v[104:105], v[40:43], off offset:32
	v_lshlrev_b32_e32 v64, 16, v168
	v_and_b32_e32 v65, 0xffff0000, v168
	v_lshlrev_b32_e32 v66, 16, v169
	v_and_b32_e32 v67, 0xffff0000, v169
	v_mul_f32_e32 v68, 0xbfb8aa3b, v64
	v_mul_f32_e32 v69, 0xbfb8aa3b, v65
	v_mul_f32_e32 v70, 0xbfb8aa3b, v66
	v_mul_f32_e32 v71, 0xbfb8aa3b, v67
	v_exp_f32_e32 v68, v68
	v_exp_f32_e32 v69, v69
	v_exp_f32_e32 v70, v70
	v_exp_f32_e32 v71, v71
	v_add_f32_e32 v68, 1.0, v68
	v_add_f32_e32 v69, 1.0, v69
	v_add_f32_e32 v70, 1.0, v70
	v_add_f32_e32 v71, 1.0, v71
	v_rcp_f32_e32 v68, v68
	v_rcp_f32_e32 v69, v69
	v_rcp_f32_e32 v70, v70
	v_rcp_f32_e32 v71, v71
	v_mul_f32_e32 v64, v68, v64
	v_mul_f32_e32 v65, v69, v65
	v_mul_f32_e32 v66, v70, v66
	v_mul_f32_e32 v67, v71, v67
	v_mul_f32_e32 v16, v16, v0
	v_mul_f32_e32 v17, v17, v0
	v_mul_f32_e32 v18, v18, v0
	v_mul_f32_e32 v19, v19, v0
	v_mul_f32_e32 v16, v16, v64
	v_mul_f32_e32 v17, v17, v65
	v_mul_f32_e32 v18, v18, v66
	v_mul_f32_e32 v19, v19, v67
	v_cvt_pk_bf16_f32 v16, v16, v17
	v_cvt_pk_bf16_f32 v17, v18, v19
	v_lshlrev_b32_e32 v64, 16, v170
	v_and_b32_e32 v65, 0xffff0000, v170
	v_lshlrev_b32_e32 v66, 16, v171
; #define LAS __attribute__((address_space(3)))
; DI void write_y(const f32x16& o0, const f32x16& o1, float scale, const bf16_t* grow, bf16_t* yrow, int h) {
; #pragma unroll
;     for (int dh = 0; dh < 2; ++dh) {
;         u32x2 w[4];
; #pragma unroll
;         for (int grp = 0; grp < 4; ++grp) {
;             const int d0 = 32 * dh + 8 * grp + 4 * h;
;             const u32x2 g = *(const u32x2*)(grow + d0);
; DI void swa_wg_unit(bf16_t* act, int b, int hk, int Qb, const float* sinks_l, LAS const float* tabS, LAS unsigned char* lds, int wid, int lane) {
;     ...
;     for (int g = 0; g < 4; ++g) {
;         const int hq = 4 * hk + g;
;         LAS const float* tab = tabS + hq * 128;
;         bf16x8 qf[4]; load_q(qf, act + rowq * PITCH + C_QC + hq * 64, h);
;         f32x16 o0, o1;
; #pragma unroll
;         for (int i = 0; i < 16; ++i) { o0[i] = 0.f; o1[i] = 0.f; }
;         float m = sinks_l[hq] * LOG2E, l = (h == 0) ? 1.0f : 0.f;
;         for (int t = tlo; t <= (q0 >> 6); ++t) {
	v_and_b32_e32 v67, 0xffff0000, v171
	v_mul_f32_e32 v68, 0xbfb8aa3b, v64
	v_mul_f32_e32 v69, 0xbfb8aa3b, v65
	v_mul_f32_e32 v70, 0xbfb8aa3b, v66
	v_mul_f32_e32 v71, 0xbfb8aa3b, v67
	v_exp_f32_e32 v68, v68
	v_exp_f32_e32 v69, v69
	v_exp_f32_e32 v70, v70
	v_exp_f32_e32 v71, v71
	v_add_f32_e32 v68, 1.0, v68
	v_add_f32_e32 v69, 1.0, v69
	v_add_f32_e32 v70, 1.0, v70
	v_add_f32_e32 v71, 1.0, v71
	v_rcp_f32_e32 v68, v68
	v_rcp_f32_e32 v69, v69
	v_rcp_f32_e32 v70, v70
	v_rcp_f32_e32 v71, v71
	v_mul_f32_e32 v64, v68, v64
	v_mul_f32_e32 v65, v69, v65
	v_mul_f32_e32 v66, v70, v66
	v_mul_f32_e32 v67, v71, v67
	v_mul_f32_e32 v20, v20, v0
	v_mul_f32_e32 v21, v21, v0
	v_mul_f32_e32 v22, v22, v0
	v_mul_f32_e32 v23, v23, v0
	v_mul_f32_e32 v20, v20, v64
	v_mul_f32_e32 v21, v21, v65
	v_mul_f32_e32 v22, v22, v66
	v_mul_f32_e32 v23, v23, v67
	v_cvt_pk_bf16_f32 v18, v20, v21
	v_cvt_pk_bf16_f32 v19, v22, v23
	s_nop 1
	v_permlane32_swap_b32_e32 v16, v18
	v_permlane32_swap_b32_e32 v17, v19
	global_store_dwordx4 v[104:105], v[16:19], off offset:64
	v_lshlrev_b32_e32 v64, 16, v172
	v_and_b32_e32 v65, 0xffff0000, v172
	v_lshlrev_b32_e32 v66, 16, v173
	v_and_b32_e32 v67, 0xffff0000, v173
	v_mul_f32_e32 v68, 0xbfb8aa3b, v64
	v_mul_f32_e32 v69, 0xbfb8aa3b, v65
	v_mul_f32_e32 v70, 0xbfb8aa3b, v66
	v_mul_f32_e32 v71, 0xbfb8aa3b, v67
	v_exp_f32_e32 v68, v68
	v_exp_f32_e32 v69, v69
	v_exp_f32_e32 v70, v70
	v_exp_f32_e32 v71, v71
	v_add_f32_e32 v68, 1.0, v68
	v_add_f32_e32 v69, 1.0, v69
	v_add_f32_e32 v70, 1.0, v70
	v_add_f32_e32 v71, 1.0, v71
	v_rcp_f32_e32 v68, v68
	v_rcp_f32_e32 v69, v69
	v_rcp_f32_e32 v70, v70
	v_rcp_f32_e32 v71, v71
	v_mul_f32_e32 v64, v68, v64
	v_mul_f32_e32 v65, v69, v65
	v_mul_f32_e32 v66, v70, v66
	v_mul_f32_e32 v67, v71, v67
	v_mul_f32_e32 v24, v24, v0
	v_mul_f32_e32 v25, v25, v0
	v_mul_f32_e32 v26, v26, v0
	v_mul_f32_e32 v27, v27, v0
	v_mul_f32_e32 v24, v24, v64
	v_mul_f32_e32 v25, v25, v65
	v_mul_f32_e32 v26, v26, v66
	v_mul_f32_e32 v27, v27, v67
	v_cvt_pk_bf16_f32 v24, v24, v25
	v_cvt_pk_bf16_f32 v25, v26, v27
	v_lshlrev_b32_e32 v64, 16, v174
	v_and_b32_e32 v65, 0xffff0000, v174
	v_lshlrev_b32_e32 v66, 16, v175
	v_and_b32_e32 v67, 0xffff0000, v175
	v_mul_f32_e32 v68, 0xbfb8aa3b, v64
	v_mul_f32_e32 v69, 0xbfb8aa3b, v65
	v_mul_f32_e32 v70, 0xbfb8aa3b, v66
	v_mul_f32_e32 v71, 0xbfb8aa3b, v67
	v_exp_f32_e32 v68, v68
	v_exp_f32_e32 v69, v69
	v_exp_f32_e32 v70, v70
	v_exp_f32_e32 v71, v71
	v_add_f32_e32 v68, 1.0, v68
	v_add_f32_e32 v69, 1.0, v69
	v_add_f32_e32 v70, 1.0, v70
	v_add_f32_e32 v71, 1.0, v71
	v_rcp_f32_e32 v68, v68
	v_rcp_f32_e32 v69, v69
	v_rcp_f32_e32 v70, v70
	v_rcp_f32_e32 v71, v71
	v_mul_f32_e32 v64, v68, v64
	v_mul_f32_e32 v65, v69, v65
	v_mul_f32_e32 v66, v70, v66
	v_mul_f32_e32 v67, v71, v67
	v_mul_f32_e32 v28, v28, v0
	v_mul_f32_e32 v29, v29, v0
	v_mul_f32_e32 v30, v30, v0
	v_mul_f32_e32 v31, v31, v0
	v_mul_f32_e32 v28, v28, v64
	v_mul_f32_e32 v29, v29, v65
	v_mul_f32_e32 v30, v30, v66
	v_mul_f32_e32 v31, v31, v67
	v_cvt_pk_bf16_f32 v26, v28, v29
	v_cvt_pk_bf16_f32 v27, v30, v31
	s_nop 1
	v_permlane32_swap_b32_e32 v24, v26
	v_permlane32_swap_b32_e32 v25, v27
	global_store_dwordx4 v[104:105], v[24:27], off offset:96
	s_cbranch_scc1 .LBB0_360
.LBB0_378:
	s_add_i32 s10, s13, s14
	s_lshl_b32 s38, s10, 7
	v_lshl_add_u64 v[104:105], v[102:103], 0, s[38:39]
	v_mov_b32_e32 v31, 0
	s_andn2_b64 vcc, exec, s[8:9]
	v_mov_b32_e32 v30, 0
	v_mov_b32_e32 v29, 0
	v_mov_b32_e32 v28, 0
	v_mov_b32_e32 v27, 0
	v_mov_b32_e32 v26, 0
	s_waitcnt vmcnt(0)
	v_mov_b32_e32 v25, 0
	v_mov_b32_e32 v24, 0
	v_mov_b32_e32 v23, 0
	v_mov_b32_e32 v22, 0
	v_mov_b32_e32 v21, 0
	v_mov_b32_e32 v20, 0
	v_mov_b32_e32 v19, 0
	v_mov_b32_e32 v18, 0
	v_mov_b32_e32 v17, 0
	v_mov_b32_e32 v16, 0
	v_mov_b32_e32 v47, 0
	v_mov_b32_e32 v46, 0
	v_mov_b32_e32 v45, 0
	v_mov_b32_e32 v44, 0
	v_mov_b32_e32 v43, 0
	v_mov_b32_e32 v42, 0
	v_mov_b32_e32 v41, 0
	v_mov_b32_e32 v40, 0
	v_mov_b32_e32 v39, 0
	v_mov_b32_e32 v38, 0
	v_mov_b32_e32 v37, 0
	v_mov_b32_e32 v36, 0
	v_mov_b32_e32 v35, 0
	v_mov_b32_e32 v34, 0
	v_mov_b32_e32 v33, 0
	v_mov_b32_e32 v32, 0
	v_lshl_add_u64 v[142:143], v[100:101], 0, s[38:39]
	global_load_dwordx2 v[160:161], v[142:143], off
	global_load_dwordx2 v[162:163], v[142:143], off offset:16
	global_load_dwordx2 v[164:165], v[142:143], off offset:32
	global_load_dwordx2 v[166:167], v[142:143], off offset:48
	global_load_dwordx2 v[168:169], v[142:143], off offset:64
	global_load_dwordx2 v[170:171], v[142:143], off offset:80
	global_load_dwordx2 v[172:173], v[142:143], off offset:96
	global_load_dwordx2 v[174:175], v[142:143], off offset:112
	v_mov_b32_e32 v118, v108
	s_cbranch_vccnz .LBB0_377
	s_lshl_b32 s11, s10, 9
	s_add_i32 s24, s11, 0
	s_mov_b32 s11, s39
	s_add_i32 s24, s24, 0x21080
	s_lshl_b64 s[26:27], s[10:11], 2
	s_add_u32 s26, s16, s26
	s_addc_u32 s27, s17, s27
	global_load_dwordx4 v[80:83], v[104:105], off
	global_load_dwordx4 v[84:87], v[104:105], off offset:32
	global_load_dword v32, v1, s[26:27]
	global_load_dwordx4 v[88:91], v[104:105], off offset:64
	global_load_dwordx4 v[92:95], v[104:105], off offset:96
	v_mov_b32_e32 v14, v1
	v_mov_b32_e32 v15, v1
	v_mov_b32_e32 v0, v1
	v_mov_b32_e32 v2, v1
	v_mov_b32_e32 v3, v1
	v_mov_b32_e32 v4, v1
	v_mov_b32_e32 v5, v1
	v_mov_b32_e32 v6, v1
	v_mov_b32_e32 v7, v1
	v_mov_b32_e32 v8, v1
	v_mov_b32_e32 v9, v1
	v_mov_b32_e32 v10, v1
	v_mov_b32_e32 v11, v1
	v_mov_b32_e32 v12, v1
	v_mov_b32_e32 v13, v1
	v_mov_b64_e32 v[30:31], v[14:15]
	v_mov_b32_e32 v119, v117
	v_mov_b32_e32 v120, v99
	s_mov_b32 s11, s23
	v_mov_b32_e32 v121, v97
	v_mov_b32_e32 v118, v108
	v_mov_b64_e32 v[28:29], v[12:13]
	v_mov_b64_e32 v[26:27], v[10:11]
	v_mov_b64_e32 v[24:25], v[8:9]
	v_mov_b64_e32 v[22:23], v[6:7]
	v_mov_b64_e32 v[20:21], v[4:5]
	v_mov_b64_e32 v[18:19], v[2:3]
	v_mov_b64_e32 v[16:17], v[0:1]
	s_waitcnt vmcnt(2)
	v_mul_f32_e32 v122, 0x3fb8aa3b, v32
	v_mov_b64_e32 v[46:47], v[14:15]
	v_mov_b64_e32 v[44:45], v[12:13]
	v_mov_b64_e32 v[42:43], v[10:11]
	v_mov_b64_e32 v[40:41], v[8:9]
	v_mov_b64_e32 v[38:39], v[6:7]
	v_mov_b64_e32 v[36:37], v[4:5]
	v_mov_b64_e32 v[34:35], v[2:3]
	v_mov_b64_e32 v[32:33], v[0:1]
	s_branch .LBB0_381
